# mixer rms-norm row loop: next-row touch as in the FFN norm (on top of v42)
# baseline (speedup 1.0000x reference)
.LBB0_191:
	s_waitcnt vmcnt(3)
	v_mul_f32_e32 v0, v31, v31
	s_waitcnt vmcnt(2)
	v_mul_f32_e32 v42, v27, v27
	v_fmac_f32_e32 v0, v30, v30
	v_fmac_f32_e32 v42, v26, v26
	v_fmac_f32_e32 v0, v32, v32
	v_fmac_f32_e32 v42, v28, v28
	v_fmac_f32_e32 v0, v33, v33
	v_fmac_f32_e32 v42, v29, v29
	s_waitcnt vmcnt(0)
	v_pk_mul_f32 v[46:47], v[18:19], v[18:19]
	v_pk_mul_f32 v[58:59], v[22:23], v[22:23]
	v_add_f32_e32 v0, v0, v42
	v_pk_mul_f32 v[42:43], v[20:21], v[20:21]
	v_pk_mul_f32 v[44:45], v[24:25], v[24:25]
	v_mov_b32_e32 v60, v46
	v_mov_b32_e32 v61, v58
	v_mov_b32_e32 v58, v47
	v_pk_add_f32 v[46:47], v[60:61], v[58:59]
	v_mov_b32_e32 v58, v42
	v_mov_b32_e32 v59, v44
	v_pk_add_f32 v[46:47], v[58:59], v[46:47]
	v_mov_b32_e32 v44, v43
	v_pk_add_f32 v[42:43], v[44:45], v[46:47]
	s_cmpk_lt_u32 s2, 0x4000
	v_add_f32_e32 v0, v43, v0
	v_add_f32_e32 v0, v42, v0
	ds_bpermute_b32 v42, v35, v0
	s_movk_i32 s0, 0x4800
	s_cselect_b32 s0, 0x2400, s0
	s_cmpk_gt_i32 s2, 0x1fff
	s_cselect_b32 s0, s0, 0
	s_waitcnt lgkmcnt(0)
	v_add_f32_e32 v0, v0, v42
	ds_bpermute_b32 v42, v48, v0
	s_lshl_b32 s0, s0, 2
	v_readlane_b32 s1, v254, 45
	s_add_u32 s0, s1, s0
	v_readlane_b32 s1, v254, 47
	s_waitcnt lgkmcnt(0)
	v_add_f32_e32 v0, v0, v42
	ds_bpermute_b32 v42, v49, v0
	s_addc_u32 s1, s1, 0
	s_add_u32 s4, s0, 0x3000
	s_addc_u32 s5, s1, 0
	s_add_u32 s6, s0, 0x4000
	s_waitcnt lgkmcnt(0)
	v_add_f32_e32 v0, v0, v42
	ds_bpermute_b32 v42, v50, v0
	s_addc_u32 s7, s1, 0
	global_load_dwordx4 v[100:103], v56, s[6:7]
	global_load_dwordx4 v[104:107], v56, s[4:5]
	global_load_dwordx4 v[108:111], v53, s[6:7]
	global_load_dwordx4 v[112:115], v53, s[4:5]
	global_load_dwordx4 v[116:119], v54, s[6:7]
	global_load_dwordx4 v[120:123], v54, s[4:5]
	global_load_dwordx4 v[124:127], v55, s[6:7]
	global_load_dwordx4 v[128:131], v55, s[4:5]
	v_readlane_b32 s36, v249, 52
	s_add_i32 s36, s2, s36
	s_cmpk_gt_i32 s36, 0x41ff
	s_cbranch_scc1 .Lnm_selftouch
	s_add_i32 s37, s36, 0xffffc000
	s_cmpk_lt_i32 s36, 0x4000
	s_cselect_b32 s38, s36, s37
	s_cselect_b32 s27, s79, s97
	s_cselect_b32 s26, s78, s96
	s_ashr_i32 s39, s38, 31
	s_lshl_b64 s[38:39], s[38:39], 12
	s_add_u32 s26, s26, s38
	s_addc_u32 s27, s27, s39
	s_branch .Lnm_touch
.Lnm_selftouch:
	s_mov_b64 s[26:27], s[4:5]
.Lnm_touch:
	global_load_dwordx4 v[132:135], v56, s[26:27]
	global_load_dwordx4 v[132:135], v56, s[26:27] offset:1024
	global_load_dwordx4 v[132:135], v56, s[26:27] offset:2048
	global_load_dwordx4 v[132:135], v56, s[26:27] offset:3072
	s_waitcnt lgkmcnt(0)
	v_add_f32_e32 v0, v0, v42
	ds_bpermute_b32 v42, v51, v0
	s_waitcnt lgkmcnt(0)
	v_add_f32_e32 v0, v0, v42
	ds_bpermute_b32 v42, v52, v0
	s_waitcnt lgkmcnt(0)
	v_add_f32_e32 v0, v0, v42
	v_fmamk_f32 v0, v0, 0x3a800000, v199
	v_cmp_gt_f32_e32 vcc, s21, v0
	v_mul_f32_e32 v42, 0x4f800000, v0
	s_nop 0
	v_cndmask_b32_e32 v0, v0, v42, vcc
	v_sqrt_f32_e32 v42, v0
	s_nop 0
	v_add_u32_e32 v43, -1, v42
	v_fma_f32 v44, -v43, v42, v0
	v_cmp_ge_f32_e64 s[38:39], 0, v44
	v_add_u32_e32 v44, 1, v42
	s_nop 0
	v_cndmask_b32_e64 v43, v42, v43, s[38:39]
	v_fma_f32 v42, -v44, v42, v0
	v_cmp_lt_f32_e64 s[38:39], 0, v42
	s_nop 1
	v_cndmask_b32_e64 v42, v43, v44, s[38:39]
	v_mul_f32_e32 v43, 0x37800000, v42
	v_cndmask_b32_e32 v42, v42, v43, vcc
	v_cmp_class_f32_e32 vcc, v0, v200
	s_nop 1
	v_cndmask_b32_e32 v0, v42, v0, vcc
	v_div_scale_f32 v42, s[0:1], v0, v0, 1.0
	v_rcp_f32_e32 v43, v42
	v_readlane_b32 s0, v249, 52
	v_readlane_b32 s1, v249, 53
	s_add_u32 s2, s2, s0
	v_fma_f32 v44, -v42, v43, 1.0
	v_fmac_f32_e32 v43, v44, v43
	v_div_scale_f32 v44, vcc, 1.0, v0, 1.0
	v_mul_f32_e32 v45, v44, v43
	v_fma_f32 v46, -v42, v45, v44
	v_fmac_f32_e32 v45, v46, v43
	v_fma_f32 v42, -v42, v45, v44
	v_div_fmas_f32 v42, v42, v43, v45
	v_div_fixup_f32 v0, v42, v0, 1.0
	v_pk_mul_f32 v[30:31], v[30:31], v[0:1] op_sel_hi:[1,0]
	v_pk_mul_f32 v[32:33], v[32:33], v[0:1] op_sel_hi:[1,0]
	v_pk_mul_f32 v[30:31], v[2:3], v[30:31]
	v_pk_mul_f32 v[32:33], v[4:5], v[32:33]
	v_pk_mul_f32 v[26:27], v[26:27], v[0:1] op_sel_hi:[1,0]
	v_pk_mul_f32 v[28:29], v[28:29], v[0:1] op_sel_hi:[1,0]
	v_pk_mul_f32 v[26:27], v[6:7], v[26:27]
	v_pk_mul_f32 v[28:29], v[8:9], v[28:29]
	v_pk_mul_f32 v[22:23], v[22:23], v[0:1] op_sel_hi:[1,0]
	v_pk_mul_f32 v[24:25], v[24:25], v[0:1] op_sel_hi:[1,0]
	v_pk_mul_f32 v[22:23], v[10:11], v[22:23]
	v_pk_mul_f32 v[24:25], v[12:13], v[24:25]
	v_pk_mul_f32 v[18:19], v[18:19], v[0:1] op_sel_hi:[1,0]
	v_pk_mul_f32 v[20:21], v[20:21], v[0:1] op_sel_hi:[1,0]
	v_pk_mul_f32 v[18:19], v[18:19], v[14:15]
	v_pk_mul_f32 v[20:21], v[20:21], v[16:17]
	s_addc_u32 s3, s3, s1
	v_readlane_b32 s0, v253, 22
	v_readlane_b32 s1, v253, 23
	s_cmpk_gt_i32 s2, 0x41ff
	s_waitcnt vmcnt(4)
	v_pk_add_f32 v[42:43], v[100:101], 1.0 op_sel_hi:[1,0]
	s_nop 0
	v_pk_fma_f32 v[30:31], v[42:43], v[30:31], v[104:105]
	v_pk_add_f32 v[42:43], v[102:103], 1.0 op_sel_hi:[1,0]
	v_cvt_pk_bf16_f32 v30, v30, v31
	v_pk_fma_f32 v[32:33], v[42:43], v[32:33], v[106:107]
	s_nop 0
	v_cvt_pk_bf16_f32 v31, v32, v33
	global_store_dwordx2 v[40:41], v[30:31], off
	v_pk_add_f32 v[30:31], v[108:109], 1.0 op_sel_hi:[1,0]
	s_nop 0
	v_pk_fma_f32 v[26:27], v[30:31], v[26:27], v[112:113]
	v_pk_add_f32 v[30:31], v[110:111], 1.0 op_sel_hi:[1,0]
	v_cvt_pk_bf16_f32 v26, v26, v27
	v_pk_fma_f32 v[28:29], v[30:31], v[28:29], v[114:115]
	s_nop 0
	v_cvt_pk_bf16_f32 v27, v28, v29
	global_store_dwordx2 v[40:41], v[26:27], off offset:512
	v_pk_add_f32 v[26:27], v[116:117], 1.0 op_sel_hi:[1,0]
	s_nop 0
	v_pk_fma_f32 v[22:23], v[22:23], v[26:27], v[120:121]
	v_pk_add_f32 v[26:27], v[118:119], 1.0 op_sel_hi:[1,0]
	v_cvt_pk_bf16_f32 v22, v22, v23
	v_pk_fma_f32 v[24:25], v[24:25], v[26:27], v[122:123]
	s_nop 0
	v_cvt_pk_bf16_f32 v23, v24, v25
	global_store_dwordx2 v[40:41], v[22:23], off offset:1024
	v_pk_add_f32 v[26:27], v[124:125], 1.0 op_sel_hi:[1,0]
	s_nop 0
	v_pk_fma_f32 v[18:19], v[18:19], v[26:27], v[128:129]
	v_pk_add_f32 v[22:23], v[126:127], 1.0 op_sel_hi:[1,0]
	v_cvt_pk_bf16_f32 v18, v18, v19
	v_pk_fma_f32 v[20:21], v[20:21], v[22:23], v[130:131]
	s_nop 0
	v_cvt_pk_bf16_f32 v19, v20, v21
	global_store_dwordx2 v[40:41], v[18:19], off offset:1536
	v_lshl_add_u64 v[40:41], v[40:41], 0, s[0:1]
	s_cbranch_scc1 .LBB0_194
